# phase-0 boundary uses the kernel's own XCD-hierarchical grid barrier instead of the cooperative-groups grid.sync
# speedup vs baseline: 1.0057x; 1.0034x over previous
; __device__ __forceinline__ unsigned xb_add(unsigned* p, unsigned v) { return __hip_atomic_fetch_add(p, v, __ATOMIC_RELAXED, __HIP_MEMORY_SCOPE_AGENT); }
; __device__ __forceinline__ void xcd_barrier(const XcdBarrier& b) {
;   asm volatile("s_waitcnt vmcnt(0)" ::: "memory");
;   __syncthreads();
;   if (threadIdx.x == 0) {
;     unsigned* bar = b.bar;
;     __builtin_amdgcn_s_waitcnt(0);
;     unsigned nloc = b.st[0], nx = b.st[1];
;     if (nloc == 0u) { xcd_barrier_complete(bar, b.x, nloc, nx); b.st[0] = nloc; b.st[1] = nx; }
;     const unsigned old = xb_add(&bar[XB_XSUB(b.x)], 1u);
; __global__ void __launch_bounds__(512, 2) fwd_megakernel(Params p, int ph_lo, int ph_hi) {
;     ...
;     if (ph < ph_hi) {
;       if (ph == 0) grid.sync();
;       else xcd_barrier(xb);
;     }
.LBB0_961:
	s_waitcnt vmcnt(0)
	s_waitcnt vmcnt(0) lgkmcnt(0)
	s_barrier
	s_mov_b64 s[0:1], exec
	v_readlane_b32 s2, v252, 5
	v_readlane_b32 s3, v252, 6
	s_and_b64 s[2:3], s[0:1], s[2:3]
	s_mov_b64 exec, s[2:3]
	s_cbranch_execz .LBB0_1014
	s_add_i32 s12, 0, 0x20000
	v_mov_b32_e32 v0, s12
	s_waitcnt vmcnt(0) expcnt(0) lgkmcnt(0)
	ds_read_b32 v2, v0
	v_readlane_b32 s2, v254, 4
	s_waitcnt lgkmcnt(0)
	v_cmp_ne_u32_e32 vcc, 0, v2
	v_mov_b32_e32 v0, s2
	ds_read_b32 v0, v0
	s_cbranch_vccnz .LBB0_978
	s_mov_b32 s13, 1
	s_branch .LBB0_966
